# norm phase: H row loads marked non-temporal (H is not re-read before being evicted)
# speedup vs baseline: 1.0129x; 1.0009x over previous
; __global__ void __launch_bounds__(512) mk_fwd(Params P) {
;     ...
;             for (int row = gw; row < M; row += NGW) {
;                 const int bi = row / TB, rr = row - bi * TB, mrow = rr < CTXL ? 4 : bi;
;                 const float* sh = modn + (size_t)mrow * NMOD;
;                 f32x4* hr = (f32x4*)(H + (size_t)row * DM) + lane; f32x4 v[4];
; #pragma unroll
;                 for (int j = 0; j < 4; ++j) v[j] = hr[64 * j];
.LBB0_464:
	s_mul_hi_i32 s11, s10, 0x78787879
	s_lshr_b32 s12, s11, 31
	s_ashr_i32 s18, s11, 11
	s_add_i32 s18, s18, s12
	s_mul_i32 s11, s18, 0xffffef00
	s_add_i32 s11, s11, s10
	s_cmpk_lt_i32 s11, 0x100
	s_cselect_b64 s[12:13], -1, 0
	s_ashr_i32 s11, s10, 31
	s_lshl_b64 s[14:15], s[10:11], 12
	v_lshl_add_u64 v[22:23], v[16:17], 0, s[14:15]
	flat_load_dwordx4 v[12:15], v[22:23] nt
	flat_load_dwordx4 v[8:11], v[22:23] offset:1024 nt
	flat_load_dwordx4 v[4:7], v[22:23] offset:2048 nt
	s_waitcnt lgkmcnt(0)
	flat_load_dwordx4 v[0:3], v[22:23] offset:3072 nt
	s_and_b64 s[14:15], s[8:9], s[12:13]
	s_andn2_b64 vcc, exec, s[14:15]
	s_cbranch_vccnz .LBB0_463
	s_mul_i32 s19, s18, 0x1100
	s_lshl_b32 s14, s18, 8
	s_sub_i32 s19, s10, s19
	s_ashr_i32 s15, s14, 31
	s_ashr_i32 s20, s19, 31
	s_add_u32 s14, s14, s19
	s_addc_u32 s15, s15, s20
	s_lshl_b64 s[14:15], s[14:15], 12
	v_lshl_add_u64 v[24:25], v[20:21], 0, s[14:15]
	s_mov_b32 s14, s3
